# FFN gate|up GEMMs: next-unit coordinates by incremental wgid (+32 per round) instead of StaticOrder's divisions
# speedup vs baseline: 1.0028x; 1.0011x over previous
;     __host__ __device__ bool next(int i, Unit& u) const {
; template <class Epi, class Sched, bool ALIGN_EPI = false, bool SP2 = false>
; __device__ __forceinline__ void gemm_phase(PG8_LAS unsigned char* lds, const Gemm g, const Sched& S, const Epi& E) {
;     int tid_ = threadIdx.x; asm volatile("" : "+v"(tid_));
;     const int tid = tid_, wid = __builtin_amdgcn_readfirstlane(tid >> 6), lane = tid & 63, wr = wid >> 2, wc = wid & 3, fr = lane & 15, fq = lane >> 4;
;     int K_ = g.K; asm volatile("" : "+s"(K_));
;     const int K = K_, nt = K / BK;
;     unsigned voffA[2], voffB[2];
; #pragma unroll
;     for (int i = 0; i < 2; ++i) { int R, C; stage_rc(tid * 16 + i * 8192, R, C); const int Rb = Epi::PERM ? ((R & ~31) + perm32(R & 31)) : R;
;         voffA[i] = (unsigned)(R * K + C) * 2u; voffB[i] = (unsigned)(Rb * K + C) * 2u; }
;     const size_t kstep = (size_t)(BK * 2);
;     const size_t hstep = (size_t)HALF * K * 2;
;     const size_t tstep = 2 * hstep;
;     const unsigned ldsw = (unsigned)wid * 1024u;
;     const int aoff = lds_byte(wr * 64 + fr, fq * 8), boff = lds_byte(wc * 32 + fr, fq * 8);
;     ...
;     Unit cur, nxt; int ui = 0;
;     if (!S.next(0, cur)) return;
;     f32x4 acc[2][2][4][2];
; #pragma unroll
;     for (int a = 0; a < 2; ++a)
; #pragma unroll
;         for (int b = 0; b < 2; ++b)
; #pragma unroll
;             for (int m = 0; m < 4; ++m)
; #pragma unroll
;                 for (int n = 0; n < 2; ++n) acc[a][b][m][n] = (f32x4){0.f, 0.f, 0.f, 0.f};
;     bf16x8 At[4][2], B0[2][2], B1[2][2];
;     const char* cA = (const char*)g.A + (size_t)cur.pm * tstep; const char* cB = (const char*)g.Bt + (size_t)cur.pn * tstep;
;     S.a_ready(cur);
;     if constexpr (SP2) {
;         PG8_STAGE(PG8_SB(0, 0), cB, voffB); PG8_STAGE(PG8_SB(0, 1), cB + hstep, voffB); PG8_STAGE(PG8_SA(0, 0), cA, voffA); PG8_STAGE(PG8_SA(0, 1), cA + hstep, voffA);
;         if (wr == 1) PG8_BAR;
;         PG8_WAIT_V(2); PG8_BAR;
;         PG8_STAGE(PG8_SB(1, 0), cB + kstep, voffB); PG8_STAGE(PG8_SA(1, 0), cA + kstep, voffA); PG8_STAGE(PG8_SB(1, 1), cB + hstep + kstep, voffB);
;         PG8_WAIT_V(6); PG8_BAR;
;     } else {
;         PG8_STAGE(PG8_SB(0, 0), cB, voffB); PG8_STAGE(PG8_SA(0, 0), cA, voffA); PG8_STAGE(PG8_SB(0, 1), cB + hstep, voffB); PG8_STAGE(PG8_SA(0, 1), cA + hstep, voffA);
;         if (wr == 1) PG8_BAR;
;         PG8_WAIT_V(4); PG8_BAR;
.LBB0_249:
	s_cmp_lt_i32 s28, 2
	s_cselect_b64 s[4:5], -1, 0
	s_add_u32 s52, s26, 0x2900000
	s_addc_u32 s53, s27, 0
	s_add_u32 s46, s26, 0x8680000
	s_addc_u32 s47, s27, 0
	s_cmpk_eq_i32 s30, 0x100
	s_cselect_b64 s[54:55], -1, 0
	s_cmpk_lg_i32 s30, 0x100
	s_cselect_b64 s[50:51], -1, 0
	s_and_b64 s[10:11], s[4:5], s[6:7]
	s_andn2_b64 vcc, exec, s[10:11]
	s_cbranch_vccnz .LBB0_291
	s_mov_b32 s86, -1
	s_mov_b32 s87, 0
	s_and_b32 s88, s2, 7
	s_mul_i32 s88, s88, 0xbb
	s_lshr_b32 s94, s2, 3
	s_add_i32 s94, s94, s88
	v_lshlrev_b32_e32 v236, 4, v192
	v_mov_b32_e32 v237, 0
	v_lshl_add_u64 v[236:237], s[44:45], 0, v[236:237]
	v_mov_b32_e32 v12, v192
	s_movk_i32 s6, 0x400
	v_readfirstlane_b32 s9, v12
	s_cmpk_gt_i32 s2, 0x5d7
	s_cbranch_scc1 .LBB0_271
	v_lshlrev_b32_e32 v0, 4, v12
	v_add_u32_e32 v1, 0x2000, v0
	v_ashrrev_i32_e32 v2, 31, v1
	v_lshrrev_b32_e32 v2, 22, v2
	v_add_u32_e32 v2, v1, v2
	v_ashrrev_i32_e32 v2, 10, v2
	v_mul_i32_i24_e32 v3, 0x400, v2
	v_sub_u32_e32 v1, v1, v3
	v_lshrrev_b32_e32 v3, 4, v1
	v_bitop3_b32 v1, v3, v1, 32 bitop3:0x6c
	v_ashrrev_i32_e32 v3, 31, v1
	v_lshrrev_b32_e32 v3, 26, v3
	v_add_u32_e32 v3, v1, v3
	v_lshlrev_b32_e32 v5, 3, v2
	v_ashrrev_i32_e32 v4, 6, v3
	v_and_b32_e32 v5, -16, v5
	v_lshlrev_b32_e32 v2, 5, v2
	v_add_u32_e32 v5, v4, v5
	v_and_b32_e32 v13, 32, v2
	v_and_b32_e32 v2, 0xc0, v3
	v_and_b32_e32 v4, 3, v4
	s_mov_b32 s4, 0x7fffffe0
	v_lshrrev_b32_e32 v6, 2, v5
	v_lshlrev_b32_e32 v7, 1, v5
	v_sub_u32_e32 v1, v1, v2
	v_mov_b32_e32 v2, 1
	v_and_or_b32 v4, v5, s4, v4
	v_and_b32_e32 v6, 4, v6
	v_and_b32_e32 v7, 24, v7
	v_ashrrev_i16_sdwa v1, v2, sext(v1) dst_sel:DWORD dst_unused:UNUSED_PAD src0_sel:DWORD src1_sel:BYTE_0
	v_or3_b32 v4, v4, v6, v7
	v_bfe_i32 v14, v1, 0, 16
	v_mul_lo_u32 v4, v4, s6
	v_add_u32_e32 v1, v13, v14
	v_mul_lo_u32 v15, v5, s6
	v_add_lshl_u32 v130, v4, v1, 1
	v_add_lshl_u32 v132, v1, v15, 1
	v_bfe_i32 v1, v12, 27, 1
	v_lshrrev_b32_e32 v1, 22, v1
	v_add_u32_e32 v1, v0, v1
	v_and_b32_e32 v1, 0xfffffc00, v1
	v_sub_u32_e32 v0, v0, v1
	v_lshrrev_b32_e32 v1, 4, v0
	v_ashrrev_i32_e32 v4, 31, v12
	v_bitop3_b32 v0, v1, v0, 32 bitop3:0x6c
	v_lshrrev_b32_e32 v4, 26, v4
	v_ashrrev_i32_e32 v1, 31, v0
	v_add_u32_e32 v4, v12, v4
	v_lshrrev_b32_e32 v1, 26, v1
	v_ashrrev_i32_e32 v4, 6, v4
	v_add_u32_e32 v1, v0, v1
	v_lshlrev_b32_e32 v5, 3, v4
	v_ashrrev_i32_e32 v3, 6, v1
	v_and_b32_e32 v5, -16, v5
	v_add_u32_e32 v5, v3, v5
	v_and_b32_e32 v3, 3, v3
	s_ashr_i32 s39, s2, 31
	v_and_or_b32 v3, v5, s4, v3
	s_lshr_b32 s4, s39, 29
	s_add_i32 s4, s2, s4
	s_ashr_i32 s20, s9, 6
	s_ashr_i32 s7, s6, 31
	s_ashr_i32 s5, s4, 3
	s_and_b32 s4, s4, -8
	s_ashr_i32 s21, s9, 8
	s_lshl_b64 s[12:13], s[6:7], 8
	s_lshl_b64 s[14:15], s[6:7], 9
	s_lshl_b32 s3, s20, 10
	s_sub_i32 s4, s2, s4
	s_cmp_lt_i32 s4, 0
	s_movk_i32 s49, 0xbc
	s_cselect_b32 s8, s49, 0xbb
	s_mul_i32 s4, s4, s8
	s_add_i32 s4, s4, s5
	s_mul_hi_i32 s5, s4, 0x2e8ba2e9
	s_lshr_b32 s8, s5, 31
	s_ashr_i32 s5, s5, 5
	v_and_b32_e32 v1, 0xc0, v1
	s_add_i32 s5, s5, s8
	v_lshrrev_b32_e32 v6, 2, v5
	v_lshlrev_b32_e32 v7, 1, v5
	v_sub_u32_e32 v0, v0, v1
	s_lshl_b32 s16, s5, 3
	v_and_b32_e32 v6, 4, v6
	v_and_b32_e32 v7, 24, v7
	v_lshlrev_b32_e32 v4, 5, v4
	v_ashrrev_i16_sdwa v0, v2, sext(v0) dst_sel:DWORD dst_unused:UNUSED_PAD src0_sel:DWORD src1_sel:BYTE_0
	s_sub_i32 s8, 0x44, s16
	s_mulk_i32 s5, 0xb0
	v_or3_b32 v3, v3, v6, v7
	v_and_b32_e32 v16, 32, v4
	v_bfe_i32 v17, v0, 0, 16
	s_min_u32 s17, s8, 8
	s_sub_i32 s18, s4, s5
	v_mul_lo_u32 v3, v3, s6
	v_add_u32_e32 v0, v16, v17
	s_sext_i32_i16 s4, s18
	v_cvt_f32_ubyte0_e32 v2, s17
	v_add_lshl_u32 v134, v3, v0, 1
	v_cvt_f32_i32_e32 v1, s4
	v_rcp_iflag_f32_e32 v3, v2
	v_mul_lo_u32 v18, v5, s6
	v_add_lshl_u32 v136, v0, v18, 1
	s_ashr_i32 s4, s4, 30
	v_mul_f32_e32 v0, v1, v3
	v_trunc_f32_e32 v0, v0
	v_fma_f32 v1, -v0, v2, v1
	v_cvt_i32_f32_e32 v0, v0
	s_or_b32 s8, s4, 1
	v_cmp_ge_f32_e64 s[4:5], |v1|, v2
	s_and_b64 s[4:5], s[4:5], exec
	s_cselect_b32 s4, s8, 0
	v_readfirstlane_b32 s5, v0
	s_add_i32 s8, s5, s4
	s_mul_i32 s4, s8, s17
	s_sub_i32 s4, s18, s4
	s_sext_i32_i16 s4, s4
	s_add_i32 s4, s16, s4
	s_ashr_i32 s5, s4, 31
	s_mul_i32 s5, s14, s5
	s_mul_hi_u32 s16, s14, s4
	s_add_i32 s5, s16, s5
	s_lshr_b64 s[16:17], s[6:7], 23
	s_mul_i32 s17, s16, s4
	s_bfe_i64 s[18:19], s[8:9], 0x100000
	s_add_i32 s5, s5, s17
	s_mul_i32 s17, s14, s19
	s_mul_hi_u32 s19, s14, s18
	s_add_i32 s17, s19, s17
	s_mul_i32 s16, s16, s18
	s_add_i32 s17, s17, s16
	s_mul_i32 s16, s14, s18
	s_add_u32 s42, s26, s16
	s_addc_u32 s43, s27, s17
	s_add_i32 s56, s3, 0
	s_add_i32 m0, s56, 0x10000
	s_mul_i32 s22, s14, s4
	global_load_lds_dwordx4 v134, s[42:43]
	s_add_i32 m0, s56, 0x12000
	s_add_u32 s16, s42, s12
	global_load_lds_dwordx4 v130, s[42:43]
	s_addc_u32 s17, s43, s13
	s_add_i32 m0, s56, 0x14000
	v_mov_b32_e32 v135, 0
	global_load_lds_dwordx4 v134, s[16:17]
	s_add_i32 m0, s56, 0x16000
	s_add_u32 s40, s34, s22
	s_addc_u32 s41, s35, s5
	s_add_i32 s57, s56, 0x2000
	global_load_lds_dwordx4 v130, s[16:17]
	s_mov_b32 m0, s56
	s_add_u32 s18, s40, s12
	global_load_lds_dwordx4 v136, s[40:41]
	s_mov_b32 m0, s57
	s_addc_u32 s19, s41, s13
	s_add_i32 s58, s56, 0x4000
	global_load_lds_dwordx4 v132, s[40:41]
	s_mov_b32 m0, s58
	s_add_i32 s59, s56, 0x6000
	global_load_lds_dwordx4 v136, s[18:19]
	s_mov_b32 m0, s59
	v_mov_b32_e32 v131, v135
	global_load_lds_dwordx4 v132, s[18:19]
	v_mov_b32_e32 v137, v135
	v_mov_b32_e32 v133, v135
	s_cmp_eq_u32 s21, 1
	s_mov_b32 s60, 0
	v_lshl_add_u64 v[8:9], s[42:43], 0, v[134:135]
	v_lshl_add_u64 v[4:5], s[42:43], 0, v[130:131]
	v_lshl_add_u64 v[2:3], s[16:17], 0, v[134:135]
	v_lshl_add_u64 v[0:1], s[16:17], 0, v[130:131]
	v_lshl_add_u64 v[6:7], s[40:41], 0, v[136:137]
	s_cselect_b64 s[16:17], -1, 0
	s_cmp_lg_u32 s21, 1
	v_lshl_add_u64 v[10:11], s[40:41], 0, v[132:133]
	s_cbranch_scc1 .LBB0_253
	s_barrier

;     __host__ __device__ bool next(int i, Unit& u) const { const int idx = first + i; if (idx >= last) return false; u.pm = idx >> 2; u.pn = idx & 3; return true; }
;     __host__ __device__ bool next(int i, Unit& u) const {
;         const long L = (long)i * G + c; if (L >= nwg) return false;
;         int wgid = (int)L; { const int q = nwg / NXCD, r = nwg % NXCD, xcd = wgid % NXCD, off = wgid / NXCD; wgid = (xcd < r ? xcd * (q + 1) : r * (q + 1) + (xcd - r) * q) + off; }
;         const int nig = WGM * nN, gid = wgid / nig, fm = gid * WGM, gsz = (nM - fm) < WGM ? (nM - fm) : WGM;
;         u.pm = fm + ((wgid % nig) % gsz); u.pn = (wgid % nig) / gsz; return true;
;     }
.LBB0_256:
	s_add_i32 s60, s60, 1
	s_cmp_lg_u32 s65, 0x100
	s_cbranch_scc1 .Lsn_orig_p1
	s_lshl_b32 s88, s60, 8
	s_add_i32 s88, s88, s2
	s_add_i32 s94, s94, 32
	s_cmp_lt_u32 s88, 0x5d8
	s_cselect_b64 s[8:9], -1, 0
	s_mul_hi_u32 s89, s94, 0x2e8ba2e9
	s_lshr_b32 s89, s89, 5
	s_mul_i32 s90, s89, 0xb0
	s_sub_i32 s90, s94, s90
	s_lshl_b32 s89, s89, 3
	s_cmp_eq_u32 s89, 64
	s_cselect_b32 s91, 2, 3
	s_lshr_b32 s69, s90, s91
	s_lshl_b32 s91, s69, s91
	s_sub_i32 s90, s90, s91
	s_add_i32 s70, s89, s90
	s_branch .LBB0_258
.Lsn_orig_p1:
	s_mul_i32 s6, s60, s64
	s_mul_hi_u32 s7, s60, s65
	s_add_i32 s7, s7, s6
	s_mul_i32 s6, s60, s65
	s_add_u32 s6, s6, s2
	s_addc_u32 s7, s7, s39
	v_cmp_gt_i64_e32 vcc, s[6:7], v[146:147]
	v_cmp_lt_i64_e64 s[8:9], s[6:7], v[144:145]
	s_cbranch_vccnz .LBB0_258
	s_ashr_i32 s7, s6, 31
	s_lshr_b32 s7, s7, 29
	s_add_i32 s7, s6, s7
	s_ashr_i32 s33, s7, 3
	s_and_b32 s7, s7, -8
	s_sub_i32 s6, s6, s7
	s_cmp_lt_i32 s6, 0
	s_cselect_b32 s7, s49, 0xbb
	s_mul_i32 s6, s6, s7
	s_add_i32 s6, s6, s33
	s_mul_hi_i32 s7, s6, 0x2e8ba2e9
	s_lshr_b32 s33, s7, 31
	s_ashr_i32 s7, s7, 5
	s_add_i32 s7, s7, s33
	s_lshl_b32 s33, s7, 3
	s_sub_i32 s36, 0x44, s33
	s_min_i32 s36, s36, 8
	s_abs_i32 s37, s36
	v_cvt_f32_u32_e32 v0, s37
	s_sub_i32 s69, 0, s37
	s_mulk_i32 s7, 0xb0
	s_sub_i32 s6, s6, s7
	v_rcp_iflag_f32_e32 v0, v0
	s_abs_i32 s7, s6
	s_xor_b32 s38, s6, s36
	s_ashr_i32 s38, s38, 31
	v_mul_f32_e32 v0, 0x4f7ffffe, v0
	v_cvt_u32_f32_e32 v0, v0
	s_nop 0
	v_readfirstlane_b32 s70, v0
	s_mul_i32 s69, s69, s70
	s_mul_hi_u32 s69, s70, s69
	s_add_i32 s70, s70, s69
	s_mul_hi_u32 s69, s7, s70
	s_mul_i32 s70, s69, s37
	s_sub_i32 s7, s7, s70
	s_add_i32 s71, s69, 1
	s_sub_i32 s70, s7, s37
	s_cmp_ge_u32 s7, s37
	s_cselect_b32 s69, s71, s69
	s_cselect_b32 s7, s70, s7
	s_add_i32 s70, s69, 1
	s_cmp_ge_u32 s7, s37
	s_cselect_b32 s7, s70, s69
	s_xor_b32 s7, s7, s38
	s_sub_i32 s69, s7, s38
	s_mul_i32 s7, s69, s36
	s_sub_i32 s6, s6, s7
	s_add_i32 s70, s33, s6

;     __host__ __device__ bool next(int i, Unit& u) const {
; template <class Epi, class Sched, bool ALIGN_EPI = false, bool SP2 = false>
; __device__ __forceinline__ void gemm_phase(PG8_LAS unsigned char* lds, const Gemm g, const Sched& S, const Epi& E) {
;     int tid_ = threadIdx.x; asm volatile("" : "+v"(tid_));
;     const int tid = tid_, wid = __builtin_amdgcn_readfirstlane(tid >> 6), lane = tid & 63, wr = wid >> 2, wc = wid & 3, fr = lane & 15, fq = lane >> 4;
;     int K_ = g.K; asm volatile("" : "+s"(K_));
;     const int K = K_, nt = K / BK;
;     unsigned voffA[2], voffB[2];
; #pragma unroll
;     for (int i = 0; i < 2; ++i) { int R, C; stage_rc(tid * 16 + i * 8192, R, C); const int Rb = Epi::PERM ? ((R & ~31) + perm32(R & 31)) : R;
;         voffA[i] = (unsigned)(R * K + C) * 2u; voffB[i] = (unsigned)(Rb * K + C) * 2u; }
;     const size_t kstep = (size_t)(BK * 2);
;     const size_t hstep = (size_t)HALF * K * 2;
;     const size_t tstep = 2 * hstep;
;     const unsigned ldsw = (unsigned)wid * 1024u;
;     const int aoff = lds_byte(wr * 64 + fr, fq * 8), boff = lds_byte(wc * 32 + fr, fq * 8);
;     ...
;     Unit cur, nxt; int ui = 0;
;     if (!S.next(0, cur)) return;
;     f32x4 acc[2][2][4][2];
; #pragma unroll
;     for (int a = 0; a < 2; ++a)
; #pragma unroll
;         for (int b = 0; b < 2; ++b)
; #pragma unroll
;             for (int m = 0; m < 4; ++m)
; #pragma unroll
;                 for (int n = 0; n < 2; ++n) acc[a][b][m][n] = (f32x4){0.f, 0.f, 0.f, 0.f};
;     bf16x8 At[4][2], B0[2][2], B1[2][2];
;     const char* cA = (const char*)g.A + (size_t)cur.pm * tstep; const char* cB = (const char*)g.Bt + (size_t)cur.pn * tstep;
;     S.a_ready(cur);
;     if constexpr (SP2) {
;         PG8_STAGE(PG8_SB(0, 0), cB, voffB); PG8_STAGE(PG8_SB(0, 1), cB + hstep, voffB); PG8_STAGE(PG8_SA(0, 0), cA, voffA); PG8_STAGE(PG8_SA(0, 1), cA + hstep, voffA);
;         if (wr == 1) PG8_BAR;
;         PG8_WAIT_V(2); PG8_BAR;
;         PG8_STAGE(PG8_SB(1, 0), cB + kstep, voffB); PG8_STAGE(PG8_SA(1, 0), cA + kstep, voffA); PG8_STAGE(PG8_SB(1, 1), cB + hstep + kstep, voffB);
;         PG8_WAIT_V(6); PG8_BAR;
;     } else {
;         PG8_STAGE(PG8_SB(0, 0), cB, voffB); PG8_STAGE(PG8_SA(0, 0), cA, voffA); PG8_STAGE(PG8_SB(0, 1), cB + hstep, voffB); PG8_STAGE(PG8_SA(0, 1), cA + hstep, voffA);
;         if (wr == 1) PG8_BAR;
;         PG8_WAIT_V(4); PG8_BAR;
.LBB0_999:
	s_cmp_lt_i32 s28, 7
	s_cselect_b64 s[4:5], -1, 0
	s_and_b64 s[8:9], s[4:5], s[0:1]
	s_andn2_b64 vcc, exec, s[8:9]
	s_cbranch_vccnz .LBB0_1041
	s_mov_b32 s86, -1
	s_mov_b32 s87, 0
	s_and_b32 s88, s2, 7
	s_mul_i32 s88, s88, 0xbb
	s_lshr_b32 s94, s2, 3
	s_add_i32 s94, s94, s88
	v_lshlrev_b32_e32 v236, 4, v192
	v_mov_b32_e32 v237, 0
	v_lshl_add_u64 v[236:237], s[44:45], 0, v[236:237]
	v_mov_b32_e32 v12, v192
	s_movk_i32 s0, 0x400
	v_readfirstlane_b32 s7, v12
	s_cmpk_gt_i32 s2, 0x5d7
	s_cbranch_scc1 .LBB0_1021
	v_lshlrev_b32_e32 v0, 4, v12
	v_add_u32_e32 v1, 0x2000, v0
	s_waitcnt lgkmcnt(0)
	v_ashrrev_i32_e32 v2, 31, v1
	v_lshrrev_b32_e32 v2, 22, v2
	v_add_u32_e32 v2, v1, v2
	v_ashrrev_i32_e32 v2, 10, v2
	v_mul_i32_i24_e32 v3, 0x400, v2
	v_sub_u32_e32 v1, v1, v3
	v_lshrrev_b32_e32 v3, 4, v1
	v_bitop3_b32 v1, v3, v1, 32 bitop3:0x6c
	v_ashrrev_i32_e32 v3, 31, v1
	v_lshrrev_b32_e32 v3, 26, v3
	v_add_u32_e32 v3, v1, v3
	v_lshlrev_b32_e32 v5, 3, v2
	v_ashrrev_i32_e32 v4, 6, v3
	v_and_b32_e32 v5, -16, v5
	v_lshlrev_b32_e32 v2, 5, v2
	v_add_u32_e32 v5, v4, v5
	v_and_b32_e32 v13, 32, v2
	v_and_b32_e32 v2, 0xc0, v3
	v_and_b32_e32 v4, 3, v4
	s_mov_b32 s4, 0x7fffffe0
	v_lshrrev_b32_e32 v6, 2, v5
	v_lshlrev_b32_e32 v7, 1, v5
	v_sub_u32_e32 v1, v1, v2
	v_mov_b32_e32 v2, 1
	v_and_or_b32 v4, v5, s4, v4
	v_and_b32_e32 v6, 4, v6
	v_and_b32_e32 v7, 24, v7
	v_ashrrev_i16_sdwa v1, v2, sext(v1) dst_sel:DWORD dst_unused:UNUSED_PAD src0_sel:DWORD src1_sel:BYTE_0
	v_or3_b32 v4, v4, v6, v7
	v_bfe_i32 v14, v1, 0, 16
	v_mul_lo_u32 v4, v4, s0
	v_add_u32_e32 v1, v13, v14
	v_mul_lo_u32 v15, v5, s0
	v_add_lshl_u32 v128, v4, v1, 1
	v_add_lshl_u32 v130, v1, v15, 1
	v_bfe_i32 v1, v12, 27, 1
	v_lshrrev_b32_e32 v1, 22, v1
	v_add_u32_e32 v1, v0, v1
	v_and_b32_e32 v1, 0xfffffc00, v1
	v_sub_u32_e32 v0, v0, v1
	v_lshrrev_b32_e32 v1, 4, v0
	v_ashrrev_i32_e32 v4, 31, v12
	v_bitop3_b32 v0, v1, v0, 32 bitop3:0x6c
	v_lshrrev_b32_e32 v4, 26, v4
	v_ashrrev_i32_e32 v1, 31, v0
	v_add_u32_e32 v4, v12, v4
	v_lshrrev_b32_e32 v1, 26, v1
	v_ashrrev_i32_e32 v4, 6, v4
	v_add_u32_e32 v1, v0, v1
	v_lshlrev_b32_e32 v5, 3, v4
	s_add_u32 s3, s26, 0x1600000
	v_ashrrev_i32_e32 v3, 6, v1
	v_and_b32_e32 v5, -16, v5
	s_addc_u32 s40, s27, 0
	v_add_u32_e32 v5, v3, v5
	v_and_b32_e32 v3, 3, v3
	s_ashr_i32 s42, s2, 31
	v_and_or_b32 v3, v5, s4, v3
	s_lshr_b32 s4, s42, 29
	s_add_i32 s4, s2, s4
	s_ashr_i32 s18, s7, 6
	s_ashr_i32 s1, s0, 31
	s_ashr_i32 s5, s4, 3
	s_and_b32 s4, s4, -8
	s_ashr_i32 s19, s7, 8
	s_lshl_b64 s[10:11], s[0:1], 8
	s_lshl_b64 s[12:13], s[0:1], 9
	s_lshl_b32 s41, s18, 10
	s_sub_i32 s4, s2, s4
	s_cmp_lt_i32 s4, 0
	s_movk_i32 s43, 0xbc
	s_cselect_b32 s6, s43, 0xbb
	s_mul_i32 s4, s4, s6
	s_add_i32 s4, s4, s5
	s_mul_hi_i32 s5, s4, 0x2e8ba2e9
	s_lshr_b32 s6, s5, 31
	s_ashr_i32 s5, s5, 5
	v_and_b32_e32 v1, 0xc0, v1
	s_add_i32 s5, s5, s6
	v_lshrrev_b32_e32 v6, 2, v5
	v_lshlrev_b32_e32 v7, 1, v5
	v_sub_u32_e32 v0, v0, v1
	s_lshl_b32 s14, s5, 3
	v_and_b32_e32 v6, 4, v6
	v_and_b32_e32 v7, 24, v7
	v_lshlrev_b32_e32 v4, 5, v4
	v_ashrrev_i16_sdwa v0, v2, sext(v0) dst_sel:DWORD dst_unused:UNUSED_PAD src0_sel:DWORD src1_sel:BYTE_0
	s_sub_i32 s6, 0x44, s14
	s_mulk_i32 s5, 0xb0
	v_or3_b32 v3, v3, v6, v7
	v_and_b32_e32 v16, 32, v4
	v_bfe_i32 v17, v0, 0, 16
	s_min_u32 s15, s6, 8
	s_sub_i32 s16, s4, s5
	v_mul_lo_u32 v3, v3, s0
	v_add_u32_e32 v0, v16, v17
	s_sext_i32_i16 s4, s16
	v_cvt_f32_ubyte0_e32 v2, s15
	v_add_lshl_u32 v132, v3, v0, 1
	v_cvt_f32_i32_e32 v1, s4
	v_rcp_iflag_f32_e32 v3, v2
	v_mul_lo_u32 v18, v5, s0
	v_add_lshl_u32 v134, v0, v18, 1
	s_ashr_i32 s4, s4, 30
	v_mul_f32_e32 v0, v1, v3
	v_trunc_f32_e32 v0, v0
	v_fma_f32 v1, -v0, v2, v1
	v_cvt_i32_f32_e32 v0, v0
	s_or_b32 s6, s4, 1
	v_cmp_ge_f32_e64 s[4:5], |v1|, v2
	s_and_b64 s[4:5], s[4:5], exec
	s_cselect_b32 s4, s6, 0
	v_readfirstlane_b32 s5, v0
	s_add_i32 s6, s5, s4
	s_mul_i32 s4, s6, s15
	s_sub_i32 s4, s16, s4
	s_sext_i32_i16 s4, s4
	s_add_i32 s4, s14, s4
	s_ashr_i32 s5, s4, 31
	s_mul_i32 s5, s12, s5
	s_mul_hi_u32 s14, s12, s4
	s_add_i32 s5, s14, s5
	s_lshr_b64 s[14:15], s[0:1], 23
	s_mul_i32 s15, s14, s4
	s_bfe_i64 s[16:17], s[6:7], 0x100000
	s_add_i32 s5, s5, s15
	s_mul_i32 s15, s12, s17
	s_mul_hi_u32 s17, s12, s16
	s_add_i32 s15, s17, s15
	s_mul_i32 s14, s14, s16
	s_add_i32 s15, s15, s14
	s_mul_i32 s14, s12, s16
	s_add_u32 s38, s3, s14
	s_addc_u32 s39, s40, s15
	s_add_i32 s48, s41, 0
	s_add_i32 m0, s48, 0x10000
	s_mul_i32 s20, s12, s4
	global_load_lds_dwordx4 v132, s[38:39]
	s_add_i32 m0, s48, 0x12000
	s_add_u32 s14, s38, s10
	global_load_lds_dwordx4 v128, s[38:39]
	s_addc_u32 s15, s39, s11
	s_add_i32 m0, s48, 0x14000
	v_mov_b32_e32 v133, 0
	global_load_lds_dwordx4 v132, s[14:15]
	s_add_i32 m0, s48, 0x16000
	s_add_u32 s36, s34, s20
	s_addc_u32 s37, s35, s5
	s_add_i32 s49, s48, 0x2000
	global_load_lds_dwordx4 v128, s[14:15]
	s_mov_b32 m0, s48
	s_add_u32 s16, s36, s10
	global_load_lds_dwordx4 v134, s[36:37]
	s_mov_b32 m0, s49
	s_addc_u32 s17, s37, s11
	s_add_i32 s56, s48, 0x4000
	global_load_lds_dwordx4 v130, s[36:37]
	s_mov_b32 m0, s56
	s_add_i32 s57, s48, 0x6000
	global_load_lds_dwordx4 v134, s[16:17]
	s_mov_b32 m0, s57
	v_mov_b32_e32 v129, v133
	global_load_lds_dwordx4 v130, s[16:17]
	v_mov_b32_e32 v135, v133
	v_mov_b32_e32 v131, v133
	s_cmp_eq_u32 s19, 1
	s_mov_b32 s58, 0
	v_lshl_add_u64 v[8:9], s[38:39], 0, v[132:133]
	v_lshl_add_u64 v[4:5], s[38:39], 0, v[128:129]
	v_lshl_add_u64 v[2:3], s[14:15], 0, v[132:133]
	v_lshl_add_u64 v[0:1], s[14:15], 0, v[128:129]
	v_lshl_add_u64 v[6:7], s[36:37], 0, v[134:135]
	s_cselect_b64 s[14:15], -1, 0
	s_cmp_lg_u32 s19, 1
	v_lshl_add_u64 v[10:11], s[36:37], 0, v[130:131]
	s_cbranch_scc1 .LBB0_1003
	s_barrier

;     __host__ __device__ bool next(int i, Unit& u) const { const int idx = first + i; if (idx >= last) return false; u.pm = idx >> 2; u.pn = idx & 3; return true; }
;     __host__ __device__ bool next(int i, Unit& u) const {
;         const long L = (long)i * G + c; if (L >= nwg) return false;
;         int wgid = (int)L; { const int q = nwg / NXCD, r = nwg % NXCD, xcd = wgid % NXCD, off = wgid / NXCD; wgid = (xcd < r ? xcd * (q + 1) : r * (q + 1) + (xcd - r) * q) + off; }
;         const int nig = WGM * nN, gid = wgid / nig, fm = gid * WGM, gsz = (nM - fm) < WGM ? (nM - fm) : WGM;
;         u.pm = fm + ((wgid % nig) % gsz); u.pn = (wgid % nig) / gsz; return true;
;     }
.LBB0_1006:
	s_add_i32 s58, s58, 1
	s_cmp_lg_u32 s64, 0x100
	s_cbranch_scc1 .Lsn_orig_p6
	s_lshl_b32 s88, s58, 8
	s_add_i32 s88, s88, s2
	s_add_i32 s94, s94, 32
	s_cmp_lt_u32 s88, 0x5d8
	s_cselect_b64 s[6:7], -1, 0
	s_mul_hi_u32 s89, s94, 0x2e8ba2e9
	s_lshr_b32 s89, s89, 5
	s_mul_i32 s90, s89, 0xb0
	s_sub_i32 s90, s94, s90
	s_lshl_b32 s89, s89, 3
	s_cmp_eq_u32 s89, 64
	s_cselect_b32 s91, 2, 3
	s_lshr_b32 s68, s90, s91
	s_lshl_b32 s91, s68, s91
	s_sub_i32 s90, s90, s91
	s_add_i32 s69, s89, s90
	s_branch .LBB0_1008
.Lsn_orig_p6:
	s_mul_i32 s0, s58, s63
	s_mul_hi_u32 s1, s58, s64
	s_add_i32 s1, s1, s0
	s_mul_i32 s0, s58, s64
	s_add_u32 s0, s0, s2
	s_addc_u32 s1, s1, s42
	v_cmp_gt_i64_e32 vcc, s[0:1], v[144:145]
	v_cmp_lt_i64_e64 s[6:7], s[0:1], v[142:143]
	s_cbranch_vccnz .LBB0_1008
	s_ashr_i32 s1, s0, 31
	s_lshr_b32 s1, s1, 29
	s_add_i32 s1, s0, s1
	s_ashr_i32 s22, s1, 3
	s_and_b32 s1, s1, -8
	s_sub_i32 s0, s0, s1
	s_cmp_lt_i32 s0, 0
	s_cselect_b32 s1, s43, 0xbb
	s_mul_i32 s0, s0, s1
	s_add_i32 s0, s0, s22
	s_mul_hi_i32 s1, s0, 0x2e8ba2e9
	s_lshr_b32 s22, s1, 31
	s_ashr_i32 s1, s1, 5
	s_add_i32 s1, s1, s22
	s_lshl_b32 s22, s1, 3
	s_sub_i32 s23, 0x44, s22
	s_min_i32 s23, s23, 8
	s_abs_i32 s33, s23
	v_cvt_f32_u32_e32 v0, s33
	s_sub_i32 s69, 0, s33
	s_mulk_i32 s1, 0xb0
	s_sub_i32 s0, s0, s1
	v_rcp_iflag_f32_e32 v0, v0
	s_abs_i32 s1, s0
	s_xor_b32 s68, s0, s23
	s_ashr_i32 s68, s68, 31
	v_mul_f32_e32 v0, 0x4f7ffffe, v0
	v_cvt_u32_f32_e32 v0, v0
	s_nop 0
	v_readfirstlane_b32 s70, v0
	s_mul_i32 s69, s69, s70
	s_mul_hi_u32 s69, s70, s69
	s_add_i32 s70, s70, s69
	s_mul_hi_u32 s69, s1, s70
	s_mul_i32 s70, s69, s33
	s_sub_i32 s1, s1, s70
	s_add_i32 s71, s69, 1
	s_sub_i32 s70, s1, s33
	s_cmp_ge_u32 s1, s33
	s_cselect_b32 s69, s71, s69
	s_cselect_b32 s1, s70, s1
	s_add_i32 s70, s69, 1
	s_cmp_ge_u32 s1, s33
	s_cselect_b32 s1, s70, s69
	s_xor_b32 s1, s1, s68
	s_sub_i32 s68, s1, s68
	s_mul_i32 s1, s68, s23
	s_sub_i32 s0, s0, s1
	s_add_i32 s69, s22, s0
